# ffn_in 4x1 wave layout + private A rows refilled a full step ahead (both k-halves of A fragments read at step start, refill issued immediately, no barrier)
# baseline (speedup 1.0000x reference)
.Lf2_setup:
	v_and_b32_e32 v70, 7, v196
	v_bfe_u32 v71, v196, 4, 2
	v_bfe_u32 v72, v196, 6, 1
	v_lshl_or_b32 v73, v72, 2, v71
	v_xor_b32_e32 v82, v70, v73
	v_lshrrev_b32_e32 v73, 3, v196
	v_lshlrev_b32_e32 v73, 11, v73
	v_lshl_or_b32 v199, v82, 4, v73
	v_xor_b32_e32 v82, v70, v71
	v_bfe_u32 v73, v196, 3, 3
	v_lshrrev_b32_e32 v83, 6, v196
	v_lshl_or_b32 v73, v83, 5, v73
	v_lshlrev_b32_e32 v73, 11, v73
	v_lshl_or_b32 v206, v82, 4, v73
	v_xor_b32_e32 v207, 64, v206
	v_and_b32_e32 v70, 15, v196
	v_bfe_u32 v73, v196, 1, 3
	v_xor_b32_e32 v73, v71, v73
	v_lshlrev_b32_e32 v73, 4, v73
	v_xor_b32_e32 v82, 64, v73
	v_lshlrev_b32_e32 v70, 7, v70
	v_lshl_or_b32 v83, v83, 12, v70
	v_add_u32_e32 v80, v83, v73
	v_add_u32_e32 v81, v83, v82
	v_add_u32_e32 v144, v70, v73
	v_add_u32_e32 v145, v70, v82
	v_readfirstlane_b32 s64, v196
	s_lshr_b32 s64, s64, 6
	s_lshl_b32 s64, s64, 10
	s_cmp_eq_u32 s39, 2
	s_cbranch_scc1 .Lf2_loop
	s_lshl_b32 s30, s8, 18
	s_add_u32 s50, s6, s30
	s_addc_u32 s51, s7, 0
	s_lshl_b32 s30, s49, 18
	s_add_u32 s52, s6, s30
	s_addc_u32 s53, s7, 0
	s_lshl_b32 s30, s21, 18
	s_add_u32 s58, s19, s30
	s_addc_u32 s59, s20, 0
	s_barrier
	s_lshl_b32 m0, s64, 2
	s_add_i32 m0, m0, 0x0
	s_nop 0
	global_load_lds_dwordx4 v206, s[50:51]
	s_add_u32 s50, s50, 0x4000
	s_addc_u32 s51, s51, 0
	s_lshl_b32 m0, s64, 2
	s_add_i32 m0, m0, 0x400
	s_nop 0
	global_load_lds_dwordx4 v207, s[50:51]
	s_add_u32 s50, s50, 0x4000
	s_addc_u32 s51, s51, 0
	s_lshl_b32 m0, s64, 2
	s_add_i32 m0, m0, 0x800
	s_nop 0
	global_load_lds_dwordx4 v206, s[50:51]
	s_add_u32 s50, s50, 0x4000
	s_addc_u32 s51, s51, 0
	s_lshl_b32 m0, s64, 2
	s_add_i32 m0, m0, 0xc00
	s_nop 0
	global_load_lds_dwordx4 v207, s[50:51]
	s_sub_u32 s50, s50, 0xbf80
	s_subb_u32 s51, s51, 0
	s_lshl_b32 m0, s64, 2
	s_add_i32 m0, m0, 0x4000
	s_nop 0
	global_load_lds_dwordx4 v206, s[52:53]
	s_add_u32 s52, s52, 0x4000
	s_addc_u32 s53, s53, 0
	s_lshl_b32 m0, s64, 2
	s_add_i32 m0, m0, 0x4400
	s_nop 0
	global_load_lds_dwordx4 v207, s[52:53]
	s_add_u32 s52, s52, 0x4000
	s_addc_u32 s53, s53, 0
	s_lshl_b32 m0, s64, 2
	s_add_i32 m0, m0, 0x4800
	s_nop 0
	global_load_lds_dwordx4 v206, s[52:53]
	s_add_u32 s52, s52, 0x4000
	s_addc_u32 s53, s53, 0
	s_lshl_b32 m0, s64, 2
	s_add_i32 m0, m0, 0x4c00
	s_nop 0
	global_load_lds_dwordx4 v207, s[52:53]
	s_sub_u32 s52, s52, 0xbf80
	s_subb_u32 s53, s53, 0
	s_add_i32 m0, s64, 0x8000
	s_nop 0
	global_load_lds_dwordx4 v199, s[58:59]
	s_add_u32 s58, s58, 0x10000
	s_addc_u32 s59, s59, 0
	s_add_i32 m0, s64, 0x9000
	s_nop 0
	global_load_lds_dwordx4 v199, s[58:59]
	s_add_u32 s58, s58, 0x10000
	s_addc_u32 s59, s59, 0
	s_add_i32 m0, s64, 0xa000
	s_nop 0
	global_load_lds_dwordx4 v199, s[58:59]
	s_add_u32 s58, s58, 0x10000
	s_addc_u32 s59, s59, 0
	s_add_i32 m0, s64, 0xb000
	s_nop 0
	global_load_lds_dwordx4 v199, s[58:59]
	s_sub_u32 s58, s58, 0x2ff80
	s_subb_u32 s59, s59, 0

.Lf2_k:
	s_waitcnt vmcnt(0)
	s_barrier
	s_add_i32 m0, s64, 0xc000
	s_nop 0
	global_load_lds_dwordx4 v199, s[58:59]
	s_add_u32 s58, s58, 0x10000
	s_addc_u32 s59, s59, 0
	s_add_i32 m0, s64, 0xd000
	s_nop 0
	global_load_lds_dwordx4 v199, s[58:59]
	s_add_u32 s58, s58, 0x10000
	s_addc_u32 s59, s59, 0
	s_add_i32 m0, s64, 0xe000
	s_nop 0
	global_load_lds_dwordx4 v199, s[58:59]
	s_add_u32 s58, s58, 0x10000
	s_addc_u32 s59, s59, 0
	s_add_i32 m0, s64, 0xf000
	s_nop 0
	global_load_lds_dwordx4 v199, s[58:59]
	s_sub_u32 s58, s58, 0x2ff80
	s_subb_u32 s59, s59, 0
	ds_read_b128 v[148:151], v80 offset:0
	ds_read_b128 v[152:155], v80 offset:2048
	ds_read_b128 v[156:159], v80 offset:16384
	ds_read_b128 v[160:163], v80 offset:18432
	ds_read_b128 v[216:219], v81 offset:0
	ds_read_b128 v[220:223], v81 offset:2048
	ds_read_b128 v[242:245], v81 offset:16384
	ds_read_b128 v[76:79], v81 offset:18432
	ds_read_b128 v[164:167], v144 offset:32768
	ds_read_b128 v[168:171], v144 offset:34816
	ds_read_b128 v[174:177], v144 offset:36864
	ds_read_b128 v[182:185], v144 offset:38912
	ds_read_b128 v[188:191], v144 offset:40960
	ds_read_b128 v[192:195], v144 offset:43008
	ds_read_b128 v[208:211], v144 offset:45056
	ds_read_b128 v[212:215], v144 offset:47104
	s_waitcnt lgkmcnt(8)
	s_lshl_b32 m0, s64, 2
	s_add_i32 m0, m0, 0x0
	s_nop 0
	global_load_lds_dwordx4 v206, s[50:51]
	s_add_u32 s50, s50, 0x4000
	s_addc_u32 s51, s51, 0
	s_lshl_b32 m0, s64, 2
	s_add_i32 m0, m0, 0x400
	s_nop 0
	global_load_lds_dwordx4 v207, s[50:51]
	s_add_u32 s50, s50, 0x4000
	s_addc_u32 s51, s51, 0
	s_lshl_b32 m0, s64, 2
	s_add_i32 m0, m0, 0x800
	s_nop 0
	global_load_lds_dwordx4 v206, s[50:51]
	s_add_u32 s50, s50, 0x4000
	s_addc_u32 s51, s51, 0
	s_lshl_b32 m0, s64, 2
	s_add_i32 m0, m0, 0xc00
	s_nop 0
	global_load_lds_dwordx4 v207, s[50:51]
	s_sub_u32 s50, s50, 0xbf80
	s_subb_u32 s51, s51, 0
	s_lshl_b32 m0, s64, 2
	s_add_i32 m0, m0, 0x4000
	s_nop 0
	global_load_lds_dwordx4 v206, s[52:53]
	s_add_u32 s52, s52, 0x4000
	s_addc_u32 s53, s53, 0
	s_lshl_b32 m0, s64, 2
	s_add_i32 m0, m0, 0x4400
	s_nop 0
	global_load_lds_dwordx4 v207, s[52:53]
	s_add_u32 s52, s52, 0x4000
	s_addc_u32 s53, s53, 0
	s_lshl_b32 m0, s64, 2
	s_add_i32 m0, m0, 0x4800
	s_nop 0
	global_load_lds_dwordx4 v206, s[52:53]
	s_add_u32 s52, s52, 0x4000
	s_addc_u32 s53, s53, 0
	s_lshl_b32 m0, s64, 2
	s_add_i32 m0, m0, 0x4c00
	s_nop 0
	global_load_lds_dwordx4 v207, s[52:53]
	s_sub_u32 s52, s52, 0xbf80
	s_subb_u32 s53, s53, 0
	s_setprio 1
	s_waitcnt lgkmcnt(0)
	v_mfma_f32_16x16x32_bf16 v[62:65], v[164:167], v[148:151], v[62:65]
	v_mfma_f32_16x16x32_bf16 v[54:57], v[168:171], v[148:151], v[54:57]
	v_mfma_f32_16x16x32_bf16 v[58:61], v[174:177], v[148:151], v[58:61]
	v_mfma_f32_16x16x32_bf16 v[50:53], v[182:185], v[148:151], v[50:53]
	v_mfma_f32_16x16x32_bf16 v[46:49], v[188:191], v[148:151], v[46:49]
	v_mfma_f32_16x16x32_bf16 v[38:41], v[192:195], v[148:151], v[38:41]
	v_mfma_f32_16x16x32_bf16 v[42:45], v[208:211], v[148:151], v[42:45]
	v_mfma_f32_16x16x32_bf16 v[34:37], v[212:215], v[148:151], v[34:37]
	v_mfma_f32_16x16x32_bf16 v[30:33], v[164:167], v[152:155], v[30:33]
	v_mfma_f32_16x16x32_bf16 v[22:25], v[168:171], v[152:155], v[22:25]
	v_mfma_f32_16x16x32_bf16 v[26:29], v[174:177], v[152:155], v[26:29]
	v_mfma_f32_16x16x32_bf16 v[18:21], v[182:185], v[152:155], v[18:21]
	v_mfma_f32_16x16x32_bf16 v[14:17], v[188:191], v[152:155], v[14:17]
	v_mfma_f32_16x16x32_bf16 v[6:9], v[192:195], v[152:155], v[6:9]
	v_mfma_f32_16x16x32_bf16 v[10:13], v[208:211], v[152:155], v[10:13]
	v_mfma_f32_16x16x32_bf16 v[2:5], v[212:215], v[152:155], v[2:5]
	v_mfma_f32_16x16x32_bf16 v[66:69], v[164:167], v[156:159], v[66:69]
	v_mfma_f32_16x16x32_bf16 v[70:73], v[168:171], v[156:159], v[70:73]
	v_mfma_f32_16x16x32_bf16 v[82:85], v[174:177], v[156:159], v[82:85]
	v_mfma_f32_16x16x32_bf16 v[86:89], v[182:185], v[156:159], v[86:89]
	v_mfma_f32_16x16x32_bf16 v[90:93], v[188:191], v[156:159], v[90:93]
	v_mfma_f32_16x16x32_bf16 v[94:97], v[192:195], v[156:159], v[94:97]
	v_mfma_f32_16x16x32_bf16 v[98:101], v[208:211], v[156:159], v[98:101]
	v_mfma_f32_16x16x32_bf16 v[102:105], v[212:215], v[156:159], v[102:105]
	v_mfma_f32_16x16x32_bf16 v[106:109], v[164:167], v[160:163], v[106:109]
	v_mfma_f32_16x16x32_bf16 v[110:113], v[168:171], v[160:163], v[110:113]
	v_mfma_f32_16x16x32_bf16 v[114:117], v[174:177], v[160:163], v[114:117]
	v_mfma_f32_16x16x32_bf16 v[118:121], v[182:185], v[160:163], v[118:121]
	v_mfma_f32_16x16x32_bf16 v[122:125], v[188:191], v[160:163], v[122:125]
	v_mfma_f32_16x16x32_bf16 v[126:129], v[192:195], v[160:163], v[126:129]
	v_mfma_f32_16x16x32_bf16 v[136:139], v[208:211], v[160:163], v[136:139]
	v_mfma_f32_16x16x32_bf16 v[140:143], v[212:215], v[160:163], v[140:143]
	s_setprio 0
	ds_read_b128 v[164:167], v145 offset:32768
	ds_read_b128 v[168:171], v145 offset:34816
	ds_read_b128 v[174:177], v145 offset:36864
	ds_read_b128 v[182:185], v145 offset:38912
	ds_read_b128 v[188:191], v145 offset:40960
	ds_read_b128 v[192:195], v145 offset:43008
	ds_read_b128 v[208:211], v145 offset:45056
	ds_read_b128 v[212:215], v145 offset:47104
	s_setprio 1
	s_waitcnt lgkmcnt(0)
	v_mfma_f32_16x16x32_bf16 v[62:65], v[164:167], v[216:219], v[62:65]
	v_mfma_f32_16x16x32_bf16 v[54:57], v[168:171], v[216:219], v[54:57]
	v_mfma_f32_16x16x32_bf16 v[58:61], v[174:177], v[216:219], v[58:61]
	v_mfma_f32_16x16x32_bf16 v[50:53], v[182:185], v[216:219], v[50:53]
	v_mfma_f32_16x16x32_bf16 v[46:49], v[188:191], v[216:219], v[46:49]
	v_mfma_f32_16x16x32_bf16 v[38:41], v[192:195], v[216:219], v[38:41]
	v_mfma_f32_16x16x32_bf16 v[42:45], v[208:211], v[216:219], v[42:45]
	v_mfma_f32_16x16x32_bf16 v[34:37], v[212:215], v[216:219], v[34:37]
	v_mfma_f32_16x16x32_bf16 v[30:33], v[164:167], v[220:223], v[30:33]
	v_mfma_f32_16x16x32_bf16 v[22:25], v[168:171], v[220:223], v[22:25]
	v_mfma_f32_16x16x32_bf16 v[26:29], v[174:177], v[220:223], v[26:29]
	v_mfma_f32_16x16x32_bf16 v[18:21], v[182:185], v[220:223], v[18:21]
	v_mfma_f32_16x16x32_bf16 v[14:17], v[188:191], v[220:223], v[14:17]
	v_mfma_f32_16x16x32_bf16 v[6:9], v[192:195], v[220:223], v[6:9]
	v_mfma_f32_16x16x32_bf16 v[10:13], v[208:211], v[220:223], v[10:13]
	v_mfma_f32_16x16x32_bf16 v[2:5], v[212:215], v[220:223], v[2:5]
	v_mfma_f32_16x16x32_bf16 v[66:69], v[164:167], v[242:245], v[66:69]
	v_mfma_f32_16x16x32_bf16 v[70:73], v[168:171], v[242:245], v[70:73]
	v_mfma_f32_16x16x32_bf16 v[82:85], v[174:177], v[242:245], v[82:85]
	v_mfma_f32_16x16x32_bf16 v[86:89], v[182:185], v[242:245], v[86:89]
	v_mfma_f32_16x16x32_bf16 v[90:93], v[188:191], v[242:245], v[90:93]
	v_mfma_f32_16x16x32_bf16 v[94:97], v[192:195], v[242:245], v[94:97]
	v_mfma_f32_16x16x32_bf16 v[98:101], v[208:211], v[242:245], v[98:101]
	v_mfma_f32_16x16x32_bf16 v[102:105], v[212:215], v[242:245], v[102:105]
	v_mfma_f32_16x16x32_bf16 v[106:109], v[164:167], v[76:79], v[106:109]
	v_mfma_f32_16x16x32_bf16 v[110:113], v[168:171], v[76:79], v[110:113]
	v_mfma_f32_16x16x32_bf16 v[114:117], v[174:177], v[76:79], v[114:117]
	v_mfma_f32_16x16x32_bf16 v[118:121], v[182:185], v[76:79], v[118:121]
	v_mfma_f32_16x16x32_bf16 v[122:125], v[188:191], v[76:79], v[122:125]
	v_mfma_f32_16x16x32_bf16 v[126:129], v[192:195], v[76:79], v[126:129]
	v_mfma_f32_16x16x32_bf16 v[136:139], v[208:211], v[76:79], v[136:139]
	v_mfma_f32_16x16x32_bf16 v[140:143], v[212:215], v[76:79], v[140:143]
	s_setprio 0
	s_waitcnt vmcnt(0)
	s_barrier
	s_add_i32 m0, s64, 0x8000
	s_nop 0
	global_load_lds_dwordx4 v199, s[58:59]
	s_add_u32 s58, s58, 0x10000
	s_addc_u32 s59, s59, 0
	s_add_i32 m0, s64, 0x9000
	s_nop 0
	global_load_lds_dwordx4 v199, s[58:59]
	s_add_u32 s58, s58, 0x10000
	s_addc_u32 s59, s59, 0
	s_add_i32 m0, s64, 0xa000
	s_nop 0
	global_load_lds_dwordx4 v199, s[58:59]
	s_add_u32 s58, s58, 0x10000
	s_addc_u32 s59, s59, 0
	s_add_i32 m0, s64, 0xb000
	s_nop 0
	global_load_lds_dwordx4 v199, s[58:59]
	s_sub_u32 s58, s58, 0x2ff80
	s_subb_u32 s59, s59, 0
	ds_read_b128 v[148:151], v80 offset:0
	ds_read_b128 v[152:155], v80 offset:2048
	ds_read_b128 v[156:159], v80 offset:16384
	ds_read_b128 v[160:163], v80 offset:18432
	ds_read_b128 v[216:219], v81 offset:0
	ds_read_b128 v[220:223], v81 offset:2048
	ds_read_b128 v[242:245], v81 offset:16384
	ds_read_b128 v[76:79], v81 offset:18432
	ds_read_b128 v[164:167], v144 offset:49152
	ds_read_b128 v[168:171], v144 offset:51200
	ds_read_b128 v[174:177], v144 offset:53248
	ds_read_b128 v[182:185], v144 offset:55296
	ds_read_b128 v[188:191], v144 offset:57344
	ds_read_b128 v[192:195], v144 offset:59392
	ds_read_b128 v[208:211], v144 offset:61440
	ds_read_b128 v[212:215], v144 offset:63488
	s_waitcnt lgkmcnt(8)
	s_lshl_b32 m0, s64, 2
	s_add_i32 m0, m0, 0x0
	s_nop 0
	global_load_lds_dwordx4 v206, s[50:51]
	s_add_u32 s50, s50, 0x4000
	s_addc_u32 s51, s51, 0
	s_lshl_b32 m0, s64, 2
	s_add_i32 m0, m0, 0x400
	s_nop 0
	global_load_lds_dwordx4 v207, s[50:51]
	s_add_u32 s50, s50, 0x4000
	s_addc_u32 s51, s51, 0
	s_lshl_b32 m0, s64, 2
	s_add_i32 m0, m0, 0x800
	s_nop 0
	global_load_lds_dwordx4 v206, s[50:51]
	s_add_u32 s50, s50, 0x4000
	s_addc_u32 s51, s51, 0
	s_lshl_b32 m0, s64, 2
	s_add_i32 m0, m0, 0xc00
	s_nop 0
	global_load_lds_dwordx4 v207, s[50:51]
	s_sub_u32 s50, s50, 0xbf80
	s_subb_u32 s51, s51, 0
	s_lshl_b32 m0, s64, 2
	s_add_i32 m0, m0, 0x4000
	s_nop 0
	global_load_lds_dwordx4 v206, s[52:53]
	s_add_u32 s52, s52, 0x4000
	s_addc_u32 s53, s53, 0
	s_lshl_b32 m0, s64, 2
	s_add_i32 m0, m0, 0x4400
	s_nop 0
	global_load_lds_dwordx4 v207, s[52:53]
	s_add_u32 s52, s52, 0x4000
	s_addc_u32 s53, s53, 0
	s_lshl_b32 m0, s64, 2
	s_add_i32 m0, m0, 0x4800
	s_nop 0
	global_load_lds_dwordx4 v206, s[52:53]
	s_add_u32 s52, s52, 0x4000
	s_addc_u32 s53, s53, 0
	s_lshl_b32 m0, s64, 2
	s_add_i32 m0, m0, 0x4c00
	s_nop 0
	global_load_lds_dwordx4 v207, s[52:53]
	s_sub_u32 s52, s52, 0xbf80
	s_subb_u32 s53, s53, 0
	s_setprio 1
	s_waitcnt lgkmcnt(0)
	v_mfma_f32_16x16x32_bf16 v[62:65], v[164:167], v[148:151], v[62:65]
	v_mfma_f32_16x16x32_bf16 v[54:57], v[168:171], v[148:151], v[54:57]
	v_mfma_f32_16x16x32_bf16 v[58:61], v[174:177], v[148:151], v[58:61]
	v_mfma_f32_16x16x32_bf16 v[50:53], v[182:185], v[148:151], v[50:53]
	v_mfma_f32_16x16x32_bf16 v[46:49], v[188:191], v[148:151], v[46:49]
	v_mfma_f32_16x16x32_bf16 v[38:41], v[192:195], v[148:151], v[38:41]
	v_mfma_f32_16x16x32_bf16 v[42:45], v[208:211], v[148:151], v[42:45]
	v_mfma_f32_16x16x32_bf16 v[34:37], v[212:215], v[148:151], v[34:37]
	v_mfma_f32_16x16x32_bf16 v[30:33], v[164:167], v[152:155], v[30:33]
	v_mfma_f32_16x16x32_bf16 v[22:25], v[168:171], v[152:155], v[22:25]
	v_mfma_f32_16x16x32_bf16 v[26:29], v[174:177], v[152:155], v[26:29]
	v_mfma_f32_16x16x32_bf16 v[18:21], v[182:185], v[152:155], v[18:21]
	v_mfma_f32_16x16x32_bf16 v[14:17], v[188:191], v[152:155], v[14:17]
	v_mfma_f32_16x16x32_bf16 v[6:9], v[192:195], v[152:155], v[6:9]
	v_mfma_f32_16x16x32_bf16 v[10:13], v[208:211], v[152:155], v[10:13]
	v_mfma_f32_16x16x32_bf16 v[2:5], v[212:215], v[152:155], v[2:5]
	v_mfma_f32_16x16x32_bf16 v[66:69], v[164:167], v[156:159], v[66:69]
	v_mfma_f32_16x16x32_bf16 v[70:73], v[168:171], v[156:159], v[70:73]
	v_mfma_f32_16x16x32_bf16 v[82:85], v[174:177], v[156:159], v[82:85]
	v_mfma_f32_16x16x32_bf16 v[86:89], v[182:185], v[156:159], v[86:89]
	v_mfma_f32_16x16x32_bf16 v[90:93], v[188:191], v[156:159], v[90:93]
	v_mfma_f32_16x16x32_bf16 v[94:97], v[192:195], v[156:159], v[94:97]
	v_mfma_f32_16x16x32_bf16 v[98:101], v[208:211], v[156:159], v[98:101]
	v_mfma_f32_16x16x32_bf16 v[102:105], v[212:215], v[156:159], v[102:105]
	v_mfma_f32_16x16x32_bf16 v[106:109], v[164:167], v[160:163], v[106:109]
	v_mfma_f32_16x16x32_bf16 v[110:113], v[168:171], v[160:163], v[110:113]
	v_mfma_f32_16x16x32_bf16 v[114:117], v[174:177], v[160:163], v[114:117]
	v_mfma_f32_16x16x32_bf16 v[118:121], v[182:185], v[160:163], v[118:121]
	v_mfma_f32_16x16x32_bf16 v[122:125], v[188:191], v[160:163], v[122:125]
	v_mfma_f32_16x16x32_bf16 v[126:129], v[192:195], v[160:163], v[126:129]
	v_mfma_f32_16x16x32_bf16 v[136:139], v[208:211], v[160:163], v[136:139]
	v_mfma_f32_16x16x32_bf16 v[140:143], v[212:215], v[160:163], v[140:143]
	s_setprio 0
	ds_read_b128 v[164:167], v145 offset:49152
	ds_read_b128 v[168:171], v145 offset:51200
	ds_read_b128 v[174:177], v145 offset:53248
	ds_read_b128 v[182:185], v145 offset:55296
	ds_read_b128 v[188:191], v145 offset:57344
	ds_read_b128 v[192:195], v145 offset:59392
	ds_read_b128 v[208:211], v145 offset:61440
	ds_read_b128 v[212:215], v145 offset:63488
	s_setprio 1
	s_waitcnt lgkmcnt(0)
	v_mfma_f32_16x16x32_bf16 v[62:65], v[164:167], v[216:219], v[62:65]
	v_mfma_f32_16x16x32_bf16 v[54:57], v[168:171], v[216:219], v[54:57]
	v_mfma_f32_16x16x32_bf16 v[58:61], v[174:177], v[216:219], v[58:61]
	v_mfma_f32_16x16x32_bf16 v[50:53], v[182:185], v[216:219], v[50:53]
	v_mfma_f32_16x16x32_bf16 v[46:49], v[188:191], v[216:219], v[46:49]
	v_mfma_f32_16x16x32_bf16 v[38:41], v[192:195], v[216:219], v[38:41]
	v_mfma_f32_16x16x32_bf16 v[42:45], v[208:211], v[216:219], v[42:45]
	v_mfma_f32_16x16x32_bf16 v[34:37], v[212:215], v[216:219], v[34:37]
	v_mfma_f32_16x16x32_bf16 v[30:33], v[164:167], v[220:223], v[30:33]
	v_mfma_f32_16x16x32_bf16 v[22:25], v[168:171], v[220:223], v[22:25]
	v_mfma_f32_16x16x32_bf16 v[26:29], v[174:177], v[220:223], v[26:29]
	v_mfma_f32_16x16x32_bf16 v[18:21], v[182:185], v[220:223], v[18:21]
	v_mfma_f32_16x16x32_bf16 v[14:17], v[188:191], v[220:223], v[14:17]
	v_mfma_f32_16x16x32_bf16 v[6:9], v[192:195], v[220:223], v[6:9]
	v_mfma_f32_16x16x32_bf16 v[10:13], v[208:211], v[220:223], v[10:13]
	v_mfma_f32_16x16x32_bf16 v[2:5], v[212:215], v[220:223], v[2:5]
	v_mfma_f32_16x16x32_bf16 v[66:69], v[164:167], v[242:245], v[66:69]
	v_mfma_f32_16x16x32_bf16 v[70:73], v[168:171], v[242:245], v[70:73]
	v_mfma_f32_16x16x32_bf16 v[82:85], v[174:177], v[242:245], v[82:85]
	v_mfma_f32_16x16x32_bf16 v[86:89], v[182:185], v[242:245], v[86:89]
	v_mfma_f32_16x16x32_bf16 v[90:93], v[188:191], v[242:245], v[90:93]
	v_mfma_f32_16x16x32_bf16 v[94:97], v[192:195], v[242:245], v[94:97]
	v_mfma_f32_16x16x32_bf16 v[98:101], v[208:211], v[242:245], v[98:101]
	v_mfma_f32_16x16x32_bf16 v[102:105], v[212:215], v[242:245], v[102:105]
	v_mfma_f32_16x16x32_bf16 v[106:109], v[164:167], v[76:79], v[106:109]
	v_mfma_f32_16x16x32_bf16 v[110:113], v[168:171], v[76:79], v[110:113]
	v_mfma_f32_16x16x32_bf16 v[114:117], v[174:177], v[76:79], v[114:117]
	v_mfma_f32_16x16x32_bf16 v[118:121], v[182:185], v[76:79], v[118:121]
	v_mfma_f32_16x16x32_bf16 v[122:125], v[188:191], v[76:79], v[122:125]
	v_mfma_f32_16x16x32_bf16 v[126:129], v[192:195], v[76:79], v[126:129]
	v_mfma_f32_16x16x32_bf16 v[136:139], v[208:211], v[76:79], v[136:139]
	v_mfma_f32_16x16x32_bf16 v[140:143], v[212:215], v[76:79], v[140:143]
	s_setprio 0
	s_add_i32 s65, s65, -1
	s_cmp_lg_u32 s65, 0
	s_cbranch_scc1 .Lf2_k
	s_waitcnt vmcnt(0)
	s_barrier
	s_add_i32 m0, s64, 0xc000
	s_nop 0
	global_load_lds_dwordx4 v199, s[58:59]
	s_add_u32 s58, s58, 0x10000
	s_addc_u32 s59, s59, 0
	s_add_i32 m0, s64, 0xd000
	s_nop 0
	global_load_lds_dwordx4 v199, s[58:59]
	s_add_u32 s58, s58, 0x10000
	s_addc_u32 s59, s59, 0
	s_add_i32 m0, s64, 0xe000
	s_nop 0
	global_load_lds_dwordx4 v199, s[58:59]
	s_add_u32 s58, s58, 0x10000
	s_addc_u32 s59, s59, 0
	s_add_i32 m0, s64, 0xf000
	s_nop 0
	global_load_lds_dwordx4 v199, s[58:59]
	s_sub_u32 s58, s58, 0x2ff80
	s_subb_u32 s59, s59, 0
	ds_read_b128 v[148:151], v80 offset:0
	ds_read_b128 v[152:155], v80 offset:2048
	ds_read_b128 v[156:159], v80 offset:16384
	ds_read_b128 v[160:163], v80 offset:18432
	ds_read_b128 v[216:219], v81 offset:0
	ds_read_b128 v[220:223], v81 offset:2048
	ds_read_b128 v[242:245], v81 offset:16384
	ds_read_b128 v[76:79], v81 offset:18432
	ds_read_b128 v[164:167], v144 offset:32768
	ds_read_b128 v[168:171], v144 offset:34816
	ds_read_b128 v[174:177], v144 offset:36864
	ds_read_b128 v[182:185], v144 offset:38912
	ds_read_b128 v[188:191], v144 offset:40960
	ds_read_b128 v[192:195], v144 offset:43008
	ds_read_b128 v[208:211], v144 offset:45056
	ds_read_b128 v[212:215], v144 offset:47104
	s_waitcnt lgkmcnt(8)
	s_lshl_b32 m0, s64, 2
	s_add_i32 m0, m0, 0x0
	s_nop 0
	global_load_lds_dwordx4 v206, s[50:51]
	s_add_u32 s50, s50, 0x4000
	s_addc_u32 s51, s51, 0
	s_lshl_b32 m0, s64, 2
	s_add_i32 m0, m0, 0x400
	s_nop 0
	global_load_lds_dwordx4 v207, s[50:51]
	s_add_u32 s50, s50, 0x4000
	s_addc_u32 s51, s51, 0
	s_lshl_b32 m0, s64, 2
	s_add_i32 m0, m0, 0x800
	s_nop 0
	global_load_lds_dwordx4 v206, s[50:51]
	s_add_u32 s50, s50, 0x4000
	s_addc_u32 s51, s51, 0
	s_lshl_b32 m0, s64, 2
	s_add_i32 m0, m0, 0xc00
	s_nop 0
	global_load_lds_dwordx4 v207, s[50:51]
	s_sub_u32 s50, s50, 0xbf80
	s_subb_u32 s51, s51, 0
	s_lshl_b32 m0, s64, 2
	s_add_i32 m0, m0, 0x4000
	s_nop 0
	global_load_lds_dwordx4 v206, s[52:53]
	s_add_u32 s52, s52, 0x4000
	s_addc_u32 s53, s53, 0
	s_lshl_b32 m0, s64, 2
	s_add_i32 m0, m0, 0x4400
	s_nop 0
	global_load_lds_dwordx4 v207, s[52:53]
	s_add_u32 s52, s52, 0x4000
	s_addc_u32 s53, s53, 0
	s_lshl_b32 m0, s64, 2
	s_add_i32 m0, m0, 0x4800
	s_nop 0
	global_load_lds_dwordx4 v206, s[52:53]
	s_add_u32 s52, s52, 0x4000
	s_addc_u32 s53, s53, 0
	s_lshl_b32 m0, s64, 2
	s_add_i32 m0, m0, 0x4c00
	s_nop 0
	global_load_lds_dwordx4 v207, s[52:53]
	s_sub_u32 s52, s52, 0xbf80
	s_subb_u32 s53, s53, 0
	s_setprio 1
	s_waitcnt lgkmcnt(0)
	v_mfma_f32_16x16x32_bf16 v[62:65], v[164:167], v[148:151], v[62:65]
	v_mfma_f32_16x16x32_bf16 v[54:57], v[168:171], v[148:151], v[54:57]
	v_mfma_f32_16x16x32_bf16 v[58:61], v[174:177], v[148:151], v[58:61]
	v_mfma_f32_16x16x32_bf16 v[50:53], v[182:185], v[148:151], v[50:53]
	v_mfma_f32_16x16x32_bf16 v[46:49], v[188:191], v[148:151], v[46:49]
	v_mfma_f32_16x16x32_bf16 v[38:41], v[192:195], v[148:151], v[38:41]
	v_mfma_f32_16x16x32_bf16 v[42:45], v[208:211], v[148:151], v[42:45]
	v_mfma_f32_16x16x32_bf16 v[34:37], v[212:215], v[148:151], v[34:37]
	v_mfma_f32_16x16x32_bf16 v[30:33], v[164:167], v[152:155], v[30:33]
	v_mfma_f32_16x16x32_bf16 v[22:25], v[168:171], v[152:155], v[22:25]
	v_mfma_f32_16x16x32_bf16 v[26:29], v[174:177], v[152:155], v[26:29]
	v_mfma_f32_16x16x32_bf16 v[18:21], v[182:185], v[152:155], v[18:21]
	v_mfma_f32_16x16x32_bf16 v[14:17], v[188:191], v[152:155], v[14:17]
	v_mfma_f32_16x16x32_bf16 v[6:9], v[192:195], v[152:155], v[6:9]
	v_mfma_f32_16x16x32_bf16 v[10:13], v[208:211], v[152:155], v[10:13]
	v_mfma_f32_16x16x32_bf16 v[2:5], v[212:215], v[152:155], v[2:5]
	v_mfma_f32_16x16x32_bf16 v[66:69], v[164:167], v[156:159], v[66:69]
	v_mfma_f32_16x16x32_bf16 v[70:73], v[168:171], v[156:159], v[70:73]
	v_mfma_f32_16x16x32_bf16 v[82:85], v[174:177], v[156:159], v[82:85]
	v_mfma_f32_16x16x32_bf16 v[86:89], v[182:185], v[156:159], v[86:89]
	v_mfma_f32_16x16x32_bf16 v[90:93], v[188:191], v[156:159], v[90:93]
	v_mfma_f32_16x16x32_bf16 v[94:97], v[192:195], v[156:159], v[94:97]
	v_mfma_f32_16x16x32_bf16 v[98:101], v[208:211], v[156:159], v[98:101]
	v_mfma_f32_16x16x32_bf16 v[102:105], v[212:215], v[156:159], v[102:105]
	v_mfma_f32_16x16x32_bf16 v[106:109], v[164:167], v[160:163], v[106:109]
	v_mfma_f32_16x16x32_bf16 v[110:113], v[168:171], v[160:163], v[110:113]
	v_mfma_f32_16x16x32_bf16 v[114:117], v[174:177], v[160:163], v[114:117]
	v_mfma_f32_16x16x32_bf16 v[118:121], v[182:185], v[160:163], v[118:121]
	v_mfma_f32_16x16x32_bf16 v[122:125], v[188:191], v[160:163], v[122:125]
	v_mfma_f32_16x16x32_bf16 v[126:129], v[192:195], v[160:163], v[126:129]
	v_mfma_f32_16x16x32_bf16 v[136:139], v[208:211], v[160:163], v[136:139]
	v_mfma_f32_16x16x32_bf16 v[140:143], v[212:215], v[160:163], v[140:143]
	s_setprio 0
	ds_read_b128 v[164:167], v145 offset:32768
	ds_read_b128 v[168:171], v145 offset:34816
	ds_read_b128 v[174:177], v145 offset:36864
	ds_read_b128 v[182:185], v145 offset:38912
	ds_read_b128 v[188:191], v145 offset:40960
	ds_read_b128 v[192:195], v145 offset:43008
	ds_read_b128 v[208:211], v145 offset:45056
	ds_read_b128 v[212:215], v145 offset:47104
	s_setprio 1
	s_waitcnt lgkmcnt(0)
	v_mfma_f32_16x16x32_bf16 v[62:65], v[164:167], v[216:219], v[62:65]
	v_mfma_f32_16x16x32_bf16 v[54:57], v[168:171], v[216:219], v[54:57]
	v_mfma_f32_16x16x32_bf16 v[58:61], v[174:177], v[216:219], v[58:61]
	v_mfma_f32_16x16x32_bf16 v[50:53], v[182:185], v[216:219], v[50:53]
	v_mfma_f32_16x16x32_bf16 v[46:49], v[188:191], v[216:219], v[46:49]
	v_mfma_f32_16x16x32_bf16 v[38:41], v[192:195], v[216:219], v[38:41]
	v_mfma_f32_16x16x32_bf16 v[42:45], v[208:211], v[216:219], v[42:45]
	v_mfma_f32_16x16x32_bf16 v[34:37], v[212:215], v[216:219], v[34:37]
	v_mfma_f32_16x16x32_bf16 v[30:33], v[164:167], v[220:223], v[30:33]
	v_mfma_f32_16x16x32_bf16 v[22:25], v[168:171], v[220:223], v[22:25]
	v_mfma_f32_16x16x32_bf16 v[26:29], v[174:177], v[220:223], v[26:29]
	v_mfma_f32_16x16x32_bf16 v[18:21], v[182:185], v[220:223], v[18:21]
	v_mfma_f32_16x16x32_bf16 v[14:17], v[188:191], v[220:223], v[14:17]
	v_mfma_f32_16x16x32_bf16 v[6:9], v[192:195], v[220:223], v[6:9]
	v_mfma_f32_16x16x32_bf16 v[10:13], v[208:211], v[220:223], v[10:13]
	v_mfma_f32_16x16x32_bf16 v[2:5], v[212:215], v[220:223], v[2:5]
	v_mfma_f32_16x16x32_bf16 v[66:69], v[164:167], v[242:245], v[66:69]
	v_mfma_f32_16x16x32_bf16 v[70:73], v[168:171], v[242:245], v[70:73]
	v_mfma_f32_16x16x32_bf16 v[82:85], v[174:177], v[242:245], v[82:85]
	v_mfma_f32_16x16x32_bf16 v[86:89], v[182:185], v[242:245], v[86:89]
	v_mfma_f32_16x16x32_bf16 v[90:93], v[188:191], v[242:245], v[90:93]
	v_mfma_f32_16x16x32_bf16 v[94:97], v[192:195], v[242:245], v[94:97]
	v_mfma_f32_16x16x32_bf16 v[98:101], v[208:211], v[242:245], v[98:101]
	v_mfma_f32_16x16x32_bf16 v[102:105], v[212:215], v[242:245], v[102:105]
	v_mfma_f32_16x16x32_bf16 v[106:109], v[164:167], v[76:79], v[106:109]
	v_mfma_f32_16x16x32_bf16 v[110:113], v[168:171], v[76:79], v[110:113]
	v_mfma_f32_16x16x32_bf16 v[114:117], v[174:177], v[76:79], v[114:117]
	v_mfma_f32_16x16x32_bf16 v[118:121], v[182:185], v[76:79], v[118:121]
	v_mfma_f32_16x16x32_bf16 v[122:125], v[188:191], v[76:79], v[122:125]
	v_mfma_f32_16x16x32_bf16 v[126:129], v[192:195], v[76:79], v[126:129]
	v_mfma_f32_16x16x32_bf16 v[136:139], v[208:211], v[76:79], v[136:139]
	v_mfma_f32_16x16x32_bf16 v[140:143], v[212:215], v[76:79], v[140:143]
	s_setprio 0
	s_waitcnt vmcnt(0)
	s_barrier
	ds_read_b128 v[148:151], v80 offset:0
	ds_read_b128 v[152:155], v80 offset:2048
	ds_read_b128 v[156:159], v80 offset:16384
	ds_read_b128 v[160:163], v80 offset:18432
	ds_read_b128 v[216:219], v81 offset:0
	ds_read_b128 v[220:223], v81 offset:2048
	ds_read_b128 v[242:245], v81 offset:16384
	ds_read_b128 v[76:79], v81 offset:18432
	ds_read_b128 v[164:167], v144 offset:49152
	ds_read_b128 v[168:171], v144 offset:51200
	ds_read_b128 v[174:177], v144 offset:53248
	ds_read_b128 v[182:185], v144 offset:55296
	ds_read_b128 v[188:191], v144 offset:57344
	ds_read_b128 v[192:195], v144 offset:59392
	ds_read_b128 v[208:211], v144 offset:61440
	ds_read_b128 v[212:215], v144 offset:63488
	s_setprio 1
	s_waitcnt lgkmcnt(0)
	v_mfma_f32_16x16x32_bf16 v[62:65], v[164:167], v[148:151], v[62:65]
	v_mfma_f32_16x16x32_bf16 v[54:57], v[168:171], v[148:151], v[54:57]
	v_mfma_f32_16x16x32_bf16 v[58:61], v[174:177], v[148:151], v[58:61]
	v_mfma_f32_16x16x32_bf16 v[50:53], v[182:185], v[148:151], v[50:53]
	v_mfma_f32_16x16x32_bf16 v[46:49], v[188:191], v[148:151], v[46:49]
	v_mfma_f32_16x16x32_bf16 v[38:41], v[192:195], v[148:151], v[38:41]
	v_mfma_f32_16x16x32_bf16 v[42:45], v[208:211], v[148:151], v[42:45]
	v_mfma_f32_16x16x32_bf16 v[34:37], v[212:215], v[148:151], v[34:37]
	v_mfma_f32_16x16x32_bf16 v[30:33], v[164:167], v[152:155], v[30:33]
	v_mfma_f32_16x16x32_bf16 v[22:25], v[168:171], v[152:155], v[22:25]
	v_mfma_f32_16x16x32_bf16 v[26:29], v[174:177], v[152:155], v[26:29]
	v_mfma_f32_16x16x32_bf16 v[18:21], v[182:185], v[152:155], v[18:21]
	v_mfma_f32_16x16x32_bf16 v[14:17], v[188:191], v[152:155], v[14:17]
	v_mfma_f32_16x16x32_bf16 v[6:9], v[192:195], v[152:155], v[6:9]
	v_mfma_f32_16x16x32_bf16 v[10:13], v[208:211], v[152:155], v[10:13]
	v_mfma_f32_16x16x32_bf16 v[2:5], v[212:215], v[152:155], v[2:5]
	v_mfma_f32_16x16x32_bf16 v[66:69], v[164:167], v[156:159], v[66:69]
	v_mfma_f32_16x16x32_bf16 v[70:73], v[168:171], v[156:159], v[70:73]
	v_mfma_f32_16x16x32_bf16 v[82:85], v[174:177], v[156:159], v[82:85]
	v_mfma_f32_16x16x32_bf16 v[86:89], v[182:185], v[156:159], v[86:89]
	v_mfma_f32_16x16x32_bf16 v[90:93], v[188:191], v[156:159], v[90:93]
	v_mfma_f32_16x16x32_bf16 v[94:97], v[192:195], v[156:159], v[94:97]
	v_mfma_f32_16x16x32_bf16 v[98:101], v[208:211], v[156:159], v[98:101]
	v_mfma_f32_16x16x32_bf16 v[102:105], v[212:215], v[156:159], v[102:105]
	v_mfma_f32_16x16x32_bf16 v[106:109], v[164:167], v[160:163], v[106:109]
	v_mfma_f32_16x16x32_bf16 v[110:113], v[168:171], v[160:163], v[110:113]
	v_mfma_f32_16x16x32_bf16 v[114:117], v[174:177], v[160:163], v[114:117]
	v_mfma_f32_16x16x32_bf16 v[118:121], v[182:185], v[160:163], v[118:121]
	v_mfma_f32_16x16x32_bf16 v[122:125], v[188:191], v[160:163], v[122:125]
	v_mfma_f32_16x16x32_bf16 v[126:129], v[192:195], v[160:163], v[126:129]
	v_mfma_f32_16x16x32_bf16 v[136:139], v[208:211], v[160:163], v[136:139]
	v_mfma_f32_16x16x32_bf16 v[140:143], v[212:215], v[160:163], v[140:143]
	s_setprio 0
	ds_read_b128 v[164:167], v145 offset:49152
	ds_read_b128 v[168:171], v145 offset:51200
	ds_read_b128 v[174:177], v145 offset:53248
	ds_read_b128 v[182:185], v145 offset:55296
	ds_read_b128 v[188:191], v145 offset:57344
	ds_read_b128 v[192:195], v145 offset:59392
	ds_read_b128 v[208:211], v145 offset:61440
	ds_read_b128 v[212:215], v145 offset:63488
	s_setprio 1
	s_waitcnt lgkmcnt(0)
	v_mfma_f32_16x16x32_bf16 v[62:65], v[164:167], v[216:219], v[62:65]
	v_mfma_f32_16x16x32_bf16 v[54:57], v[168:171], v[216:219], v[54:57]
	v_mfma_f32_16x16x32_bf16 v[58:61], v[174:177], v[216:219], v[58:61]
	v_mfma_f32_16x16x32_bf16 v[50:53], v[182:185], v[216:219], v[50:53]
	v_mfma_f32_16x16x32_bf16 v[46:49], v[188:191], v[216:219], v[46:49]
	v_mfma_f32_16x16x32_bf16 v[38:41], v[192:195], v[216:219], v[38:41]
	v_mfma_f32_16x16x32_bf16 v[42:45], v[208:211], v[216:219], v[42:45]
	v_mfma_f32_16x16x32_bf16 v[34:37], v[212:215], v[216:219], v[34:37]
	v_mfma_f32_16x16x32_bf16 v[30:33], v[164:167], v[220:223], v[30:33]
	v_mfma_f32_16x16x32_bf16 v[22:25], v[168:171], v[220:223], v[22:25]
	v_mfma_f32_16x16x32_bf16 v[26:29], v[174:177], v[220:223], v[26:29]
	v_mfma_f32_16x16x32_bf16 v[18:21], v[182:185], v[220:223], v[18:21]
	v_mfma_f32_16x16x32_bf16 v[14:17], v[188:191], v[220:223], v[14:17]
	v_mfma_f32_16x16x32_bf16 v[6:9], v[192:195], v[220:223], v[6:9]
	v_mfma_f32_16x16x32_bf16 v[10:13], v[208:211], v[220:223], v[10:13]
	v_mfma_f32_16x16x32_bf16 v[2:5], v[212:215], v[220:223], v[2:5]
	v_mfma_f32_16x16x32_bf16 v[66:69], v[164:167], v[242:245], v[66:69]
	v_mfma_f32_16x16x32_bf16 v[70:73], v[168:171], v[242:245], v[70:73]
	v_mfma_f32_16x16x32_bf16 v[82:85], v[174:177], v[242:245], v[82:85]
	v_mfma_f32_16x16x32_bf16 v[86:89], v[182:185], v[242:245], v[86:89]
	v_mfma_f32_16x16x32_bf16 v[90:93], v[188:191], v[242:245], v[90:93]
	v_mfma_f32_16x16x32_bf16 v[94:97], v[192:195], v[242:245], v[94:97]
	v_mfma_f32_16x16x32_bf16 v[98:101], v[208:211], v[242:245], v[98:101]
	v_mfma_f32_16x16x32_bf16 v[102:105], v[212:215], v[242:245], v[102:105]
	v_mfma_f32_16x16x32_bf16 v[106:109], v[164:167], v[76:79], v[106:109]
	v_mfma_f32_16x16x32_bf16 v[110:113], v[168:171], v[76:79], v[110:113]
	v_mfma_f32_16x16x32_bf16 v[114:117], v[174:177], v[76:79], v[114:117]
	v_mfma_f32_16x16x32_bf16 v[118:121], v[182:185], v[76:79], v[118:121]
	v_mfma_f32_16x16x32_bf16 v[122:125], v[188:191], v[76:79], v[122:125]
	v_mfma_f32_16x16x32_bf16 v[126:129], v[192:195], v[76:79], v[126:129]
	v_mfma_f32_16x16x32_bf16 v[136:139], v[208:211], v[76:79], v[136:139]
	v_mfma_f32_16x16x32_bf16 v[140:143], v[212:215], v[76:79], v[140:143]
	s_setprio 0
	s_nop 7
	s_nop 7
	s_nop 7
	s_add_i32 s48, s48, 1
	s_mov_b32 s39, 0
	v_readlane_b32 s30, v249, 0
	s_nop 0
	s_and_b32 s31, s30, 7
	s_lshr_b32 s30, s30, 3
	s_cmp_lt_u32 s30, 32
	s_cselect_b32 s35, 6, 5
	s_cmp_lt_u32 s48, s35
	s_cbranch_scc0 .Lf2_c1_extra
	s_lshl_b32 s33, s48, 6
	s_add_i32 s33, s33, s30
	s_cmp_ge_u32 s33, 0xb0
	s_cselect_b32 s34, 1, 0
	s_mul_i32 s36, s34, 0xb0
	s_sub_i32 s33, s33, s36
	s_lshr_b32 s37, s33, 2
	s_and_b32 s33, s33, 3
	s_lshl_b32 s34, s34, 3
	s_add_i32 s33, s33, s34
	s_lshl_b32 s33, s33, 3
	s_add_i32 s36, s33, s31
	s_add_i32 s38, s36, 32
	s_branch .Lf2_c1_have

.Lf2_c1_have:
	s_mov_b32 s39, 2
	s_lshl_b32 s30, s36, 18
	s_add_u32 s50, s6, s30
	s_addc_u32 s51, s7, 0
	s_lshl_b32 s30, s38, 18
	s_add_u32 s52, s6, s30
	s_addc_u32 s53, s7, 0
	s_lshl_b32 s30, s37, 18
	s_add_u32 s58, s19, s30
	s_addc_u32 s59, s20, 0
	s_barrier
	s_lshl_b32 m0, s64, 2
	s_add_i32 m0, m0, 0x0
	s_nop 0
	global_load_lds_dwordx4 v206, s[50:51]
	s_add_u32 s50, s50, 0x4000
	s_addc_u32 s51, s51, 0
	s_lshl_b32 m0, s64, 2
	s_add_i32 m0, m0, 0x400
	s_nop 0
	global_load_lds_dwordx4 v207, s[50:51]
	s_add_u32 s50, s50, 0x4000
	s_addc_u32 s51, s51, 0
	s_lshl_b32 m0, s64, 2
	s_add_i32 m0, m0, 0x800
	s_nop 0
	global_load_lds_dwordx4 v206, s[50:51]
	s_add_u32 s50, s50, 0x4000
	s_addc_u32 s51, s51, 0
	s_lshl_b32 m0, s64, 2
	s_add_i32 m0, m0, 0xc00
	s_nop 0
	global_load_lds_dwordx4 v207, s[50:51]
	s_sub_u32 s50, s50, 0xbf80
	s_subb_u32 s51, s51, 0
	s_lshl_b32 m0, s64, 2
	s_add_i32 m0, m0, 0x4000
	s_nop 0
	global_load_lds_dwordx4 v206, s[52:53]
	s_add_u32 s52, s52, 0x4000
	s_addc_u32 s53, s53, 0
	s_lshl_b32 m0, s64, 2
	s_add_i32 m0, m0, 0x4400
	s_nop 0
	global_load_lds_dwordx4 v207, s[52:53]
	s_add_u32 s52, s52, 0x4000
	s_addc_u32 s53, s53, 0
	s_lshl_b32 m0, s64, 2
	s_add_i32 m0, m0, 0x4800
	s_nop 0
	global_load_lds_dwordx4 v206, s[52:53]
	s_add_u32 s52, s52, 0x4000
	s_addc_u32 s53, s53, 0
	s_lshl_b32 m0, s64, 2
	s_add_i32 m0, m0, 0x4c00
	s_nop 0
	global_load_lds_dwordx4 v207, s[52:53]
	s_sub_u32 s52, s52, 0xbf80
	s_subb_u32 s53, s53, 0
	s_add_i32 m0, s64, 0x8000
	s_nop 0
	global_load_lds_dwordx4 v199, s[58:59]
	s_add_u32 s58, s58, 0x10000
	s_addc_u32 s59, s59, 0
	s_add_i32 m0, s64, 0x9000
	s_nop 0
	global_load_lds_dwordx4 v199, s[58:59]
	s_add_u32 s58, s58, 0x10000
	s_addc_u32 s59, s59, 0
	s_add_i32 m0, s64, 0xa000
	s_nop 0
	global_load_lds_dwordx4 v199, s[58:59]
	s_add_u32 s58, s58, 0x10000
	s_addc_u32 s59, s59, 0
	s_add_i32 m0, s64, 0xb000
	s_nop 0
	global_load_lds_dwordx4 v199, s[58:59]
	s_sub_u32 s58, s58, 0x2ff80
	s_subb_u32 s59, s59, 0
